# GU epilogues: hoisted the 8 row-stat LDS reads to the epilogue top with counted lgkmcnt; moved the wr==0 alignment barrier after the first output row
# speedup vs baseline: 1.0205x; 1.0111x over previous
; #define LAS __attribute__((address_space(3)))
; __device__ __forceinline__ unsigned cvt_pk_bf16(float lo, float hi) { unsigned r; asm volatile("v_cvt_pk_bf16_f32 %0, %1, %2" : "=v"(r) : "v"(lo), "v"(hi)); return r; }
; #define PG8_BAR __builtin_amdgcn_s_barrier()
; #define ROW_RS(u, ai, m) row_rs_lds((ai) * 128 + wr * 64 + (m) * 16 + fr, fq)
; #define ROWLOOP for (int ai = 0; ai < 2; ++ai) _Pragma("unroll") for (int m = 0; m < 4; ++m)
; template <class Epi>
; __device__ __forceinline__ void gemm_phase(LAS unsigned char* lds, const int tid, const Gemm g, const StaticOrder& S, const Epi& E) {
;     ...
;         if (wr == 0) PG8_BAR;
;         E(acc, cur, wr, wc, fr, fq);
; __device__ __forceinline__ float row_rs_lds(int rt, int fq) {
;     extern __shared__ __attribute__((aligned(16))) unsigned char lds_raw_[];
;     const f32x4 v = *(const LAS f32x4*)((LAS unsigned char*)lds_raw_ + RS_OFF + rt * 64 + fq * 16);
;     float s = (v[0] + v[1]) + (v[2] + v[3]);
;     s = red4_sum(s);
;     return __builtin_amdgcn_rsqf(s * (1.0f / D) + EPS);
; }
; __device__ __forceinline__ u32x4 pack8(const f32x4 a, const f32x4 b) {
;     u32x4 w; w.x = cvt_pk_bf16(a[0], a[1]); w.y = cvt_pk_bf16(a[2], a[3]); w.z = cvt_pk_bf16(b[0], b[1]); w.w = cvt_pk_bf16(b[2], b[3]); return w;
; }
;     __device__ __forceinline__ void operator()(const Acc& acc, const Unit& u, int wr, int wc, int fr, int fq) const {
;         const int col0 = u.pn * 128 + wc * 32 + fq * 8;
; #pragma unroll
;         ROWLOOP {
;             const int row = ROW_OF(u, ai, m); const float rs = ROW_RS(u, ai, m); const float c1 = -rs * LOG2E, rs2 = rs * rs;
;             f32x4 o[2];
; #pragma unroll
;             for (int n = 0; n < 2; ++n) {
;                 const f32x4 gv = acc[ai][0][m][n], gu = gv * acc[ai][1][m][n], t = gv * c1; f32x4 r;
; #pragma unroll
;                 for (int e = 0; e < 4; ++e) r[e] = __builtin_amdgcn_rcpf(1.0f + __builtin_amdgcn_exp2f(t[e]));
;                 o[n] = gu * (r * rs2);
;             }
;             *(u32x4*)(act + (size_t)row * FF + col0) = pack8(o[0], o[1]);
;         }
.LBB0_266:
.LBB0_268:
	ds_read_b128 v[188:191], v154
	ds_read_b128 v[192:195], v154 offset:1024
	ds_read_b128 v[196:199], v154 offset:2048
	ds_read_b128 v[200:203], v154 offset:3072
	ds_read_b128 v[204:207], v154 offset:8192
	ds_read_b128 v[208:211], v154 offset:9216
	ds_read_b128 v[212:215], v154 offset:10240
	ds_read_b128 v[216:219], v154 offset:11264
	v_pk_mul_f32 v[112:113], v[112:113], v[116:117]
	v_pk_mul_f32 v[114:115], v[114:115], v[118:119]
	v_pk_mul_f32 v[104:105], v[104:105], v[108:109]
	v_pk_mul_f32 v[106:107], v[106:107], v[110:111]
	s_waitcnt lgkmcnt(7)
	v_add_f32_e32 v146, v188, v189
	v_add_f32_e32 v147, v190, v191
	v_add_f32_e32 v146, v146, v147
	v_mov_b32_e32 v147, v146
	s_nop 1
	v_permlane16_swap_b32_e32 v146, v147
	v_add_f32_e32 v146, v146, v147
	v_mov_b32_e32 v147, v146
	s_nop 1
	v_permlane32_swap_b32_e32 v146, v147
	v_add_f32_e32 v146, v146, v147
	v_fmamk_f32 v146, v146, 0x3a800000, v155
	v_rsq_f32_e32 v147, v146
	v_lshl_or_b32 v148, s54, 7, v152
	v_lshl_add_u32 v146, s24, 8, v150
	v_pk_mul_f32 v[96:97], v[96:97], v[100:101]
	v_mul_f32_e32 v156, 0xbfb8aa3b, v147
	v_pk_mul_f32 v[160:161], v[120:121], v[156:157] op_sel_hi:[1,0]
	v_mul_f32_e32 v158, v147, v147
	v_exp_f32_e32 v147, v160
	v_exp_f32_e32 v149, v161
	v_pk_mul_f32 v[160:161], v[122:123], v[156:157] op_sel_hi:[1,0]
	v_pk_mul_f32 v[120:121], v[124:125], v[120:121]
	v_add_f32_e32 v147, 1.0, v147
	v_exp_f32_e32 v157, v160
	v_rcp_f32_e32 v160, v147
	v_exp_f32_e32 v147, v161
	v_add_f32_e32 v149, 1.0, v149
	v_rcp_f32_e32 v161, v149
	v_add_f32_e32 v149, 1.0, v157
	v_add_f32_e32 v147, 1.0, v147
	v_rcp_f32_e32 v162, v149
	v_rcp_f32_e32 v163, v147
	v_pk_mul_f32 v[122:123], v[126:127], v[122:123]
	v_pk_mul_f32 v[124:125], v[158:159], v[160:161] op_sel_hi:[0,1]
	v_pk_mul_f32 v[120:121], v[120:121], v[124:125]
	v_pk_mul_f32 v[126:127], v[158:159], v[162:163] op_sel_hi:[0,1]
	v_pk_mul_f32 v[122:123], v[122:123], v[126:127]
	v_pk_mul_f32 v[126:127], v[116:117], v[156:157] op_sel_hi:[1,0]
	v_pk_mul_f32 v[124:125], v[118:119], v[156:157] op_sel_hi:[1,0]
	v_exp_f32_e32 v126, v126
	v_exp_f32_e32 v127, v127
	v_exp_f32_e32 v124, v124
	v_exp_f32_e32 v125, v125
	v_add_f32_e32 v126, 1.0, v126
	v_add_f32_e32 v127, 1.0, v127
	v_add_f32_e32 v124, 1.0, v124
	v_add_f32_e32 v125, 1.0, v125
	v_rcp_f32_e32 v126, v126
	v_rcp_f32_e32 v127, v127
	v_rcp_f32_e32 v124, v124
	v_rcp_f32_e32 v125, v125
	v_ashrrev_i32_e32 v149, 31, v148
	v_pk_mul_f32 v[116:117], v[158:159], v[126:127] op_sel_hi:[0,1]
	v_pk_mul_f32 v[112:113], v[112:113], v[116:117]
	v_pk_mul_f32 v[118:119], v[158:159], v[124:125] op_sel_hi:[0,1]
	v_pk_mul_f32 v[114:115], v[114:115], v[118:119]
	v_cvt_pk_bf16_f32 v116, v120, v121
	v_cvt_pk_bf16_f32 v117, v122, v123
	v_cvt_pk_bf16_f32 v118, v112, v113
	v_mov_b64_e32 v[112:113], s[10:11]
	v_cvt_pk_bf16_f32 v119, v114, v115
	v_mad_i64_i32 v[124:125], s[24:25], v146, s53, v[112:113]
	v_pk_mul_f32 v[98:99], v[98:99], v[102:103]
	v_pk_mul_f32 v[88:89], v[88:89], v[92:93]
	s_waitcnt lgkmcnt(6)
	v_add_f32_e32 v114, v192, v193
	v_add_f32_e32 v115, v194, v195
	v_add_f32_e32 v114, v114, v115
	v_mov_b32_e32 v115, v114
	s_nop 1
	v_permlane16_swap_b32_e32 v114, v115
	v_add_f32_e32 v114, v114, v115
	v_mov_b32_e32 v115, v114
	s_nop 1
	v_permlane32_swap_b32_e32 v114, v115
	v_add_f32_e32 v114, v114, v115
	v_fmamk_f32 v114, v114, 0x3a800000, v155
	v_rsq_f32_e32 v122, v114
	v_lshlrev_b64 v[114:115], 1, v[148:149]
	v_lshl_add_u64 v[120:121], v[124:125], 0, v[114:115]
	global_store_dwordx4 v[120:121], v[116:119], off
	s_and_b64 vcc, exec, s[6:7]
	s_cbranch_vccz .Lalb_1
	s_barrier
.Lalb_1:
	v_pk_mul_f32 v[90:91], v[90:91], v[94:95]
	v_pk_mul_f32 v[80:81], v[80:81], v[84:85]
	v_mul_f32_e32 v116, 0xbfb8aa3b, v122
	v_pk_mul_f32 v[118:119], v[108:109], v[116:117] op_sel_hi:[1,0]
	v_pk_mul_f32 v[82:83], v[82:83], v[86:87]
	v_exp_f32_e32 v117, v118
	v_mul_f32_e32 v118, v122, v122
	v_exp_f32_e32 v119, v119
	v_pk_mul_f32 v[72:73], v[72:73], v[76:77]
	v_pk_mul_f32 v[120:121], v[110:111], v[116:117] op_sel_hi:[1,0]
	v_add_f32_e32 v117, 1.0, v117
	v_rcp_f32_e32 v122, v117
	v_exp_f32_e32 v117, v120
	v_exp_f32_e32 v121, v121
	v_add_f32_e32 v119, 1.0, v119
	v_rcp_f32_e32 v123, v119
	v_add_f32_e32 v117, 1.0, v117
	v_rcp_f32_e32 v120, v117
	v_add_f32_e32 v117, 1.0, v121
	v_rcp_f32_e32 v121, v117
	v_pk_mul_f32 v[108:109], v[118:119], v[122:123] op_sel_hi:[0,1]
	v_pk_mul_f32 v[104:105], v[104:105], v[108:109]
	v_pk_mul_f32 v[108:109], v[102:103], v[116:117] op_sel_hi:[1,0]
	v_pk_mul_f32 v[110:111], v[118:119], v[120:121] op_sel_hi:[0,1]
	v_pk_mul_f32 v[106:107], v[106:107], v[110:111]
	v_pk_mul_f32 v[110:111], v[100:101], v[116:117] op_sel_hi:[1,0]
	v_exp_f32_e32 v108, v108
	v_exp_f32_e32 v110, v110
	v_exp_f32_e32 v111, v111
	v_exp_f32_e32 v109, v109
	v_add_f32_e32 v108, 1.0, v108
	v_add_f32_e32 v110, 1.0, v110
	v_add_f32_e32 v111, 1.0, v111
	v_add_f32_e32 v109, 1.0, v109
	v_rcp_f32_e32 v110, v110
	v_rcp_f32_e32 v111, v111
	v_rcp_f32_e32 v108, v108
	v_rcp_f32_e32 v109, v109
	v_pk_mul_f32 v[74:75], v[74:75], v[78:79]
	v_pk_mul_f32 v[100:101], v[118:119], v[110:111] op_sel_hi:[0,1]
	v_pk_mul_f32 v[64:65], v[64:65], v[68:69]
	v_pk_mul_f32 v[102:103], v[118:119], v[108:109] op_sel_hi:[0,1]
	v_pk_mul_f32 v[102:103], v[98:99], v[102:103]
	v_pk_mul_f32 v[98:99], v[96:97], v[100:101]
	v_cvt_pk_bf16_f32 v96, v104, v105
	v_cvt_pk_bf16_f32 v97, v106, v107
	v_or_b32_e32 v104, 16, v146
	v_cvt_pk_bf16_f32 v98, v98, v99
	v_cvt_pk_bf16_f32 v99, v102, v103
	v_pk_mul_f32 v[66:67], v[66:67], v[70:71]
	v_pk_mul_f32 v[56:57], v[56:57], v[60:61]
	v_pk_mul_f32 v[58:59], v[58:59], v[62:63]
	v_pk_mul_f32 v[48:49], v[48:49], v[52:53]
	s_waitcnt lgkmcnt(5)
; #define LAS __attribute__((address_space(3)))
; __device__ __forceinline__ unsigned cvt_pk_bf16(float lo, float hi) { unsigned r; asm volatile("v_cvt_pk_bf16_f32 %0, %1, %2" : "=v"(r) : "v"(lo), "v"(hi)); return r; }
; #define ROW_RS(u, ai, m) row_rs_lds((ai) * 128 + wr * 64 + (m) * 16 + fr, fq)
; #define ROWLOOP for (int ai = 0; ai < 2; ++ai) _Pragma("unroll") for (int m = 0; m < 4; ++m)
; __device__ __forceinline__ float row_rs_lds(int rt, int fq) {
;     extern __shared__ __attribute__((aligned(16))) unsigned char lds_raw_[];
;     const f32x4 v = *(const LAS f32x4*)((LAS unsigned char*)lds_raw_ + RS_OFF + rt * 64 + fq * 16);
;     float s = (v[0] + v[1]) + (v[2] + v[3]);
;     s = red4_sum(s);
;     return __builtin_amdgcn_rsqf(s * (1.0f / D) + EPS);
; }
; __device__ __forceinline__ u32x4 pack8(const f32x4 a, const f32x4 b) {
;     u32x4 w; w.x = cvt_pk_bf16(a[0], a[1]); w.y = cvt_pk_bf16(a[2], a[3]); w.z = cvt_pk_bf16(b[0], b[1]); w.w = cvt_pk_bf16(b[2], b[3]); return w;
; }
;     __device__ __forceinline__ void operator()(const Acc& acc, const Unit& u, int wr, int wc, int fr, int fq) const {
;         const int col0 = u.pn * 128 + wc * 32 + fq * 8;
; #pragma unroll
;         ROWLOOP {
;             const int row = ROW_OF(u, ai, m); const float rs = ROW_RS(u, ai, m); const float c1 = -rs * LOG2E, rs2 = rs * rs;
;             f32x4 o[2];
; #pragma unroll
;             for (int n = 0; n < 2; ++n) {
;                 const f32x4 gv = acc[ai][0][m][n], gu = gv * acc[ai][1][m][n], t = gv * c1; f32x4 r;
; #pragma unroll
;                 for (int e = 0; e < 4; ++e) r[e] = __builtin_amdgcn_rcpf(1.0f + __builtin_amdgcn_exp2f(t[e]));
;                 o[n] = gu * (r * rs2);
;             }
;             *(u32x4*)(act + (size_t)row * FF + col0) = pack8(o[0], o[1]);
;         }
	v_add_f32_e32 v100, v196, v197
	v_add_f32_e32 v101, v198, v199
	v_add_f32_e32 v100, v100, v101
	v_mov_b32_e32 v101, v100
	s_nop 1
	v_permlane16_swap_b32_e32 v100, v101
	v_add_f32_e32 v100, v100, v101
	v_mov_b32_e32 v101, v100
	s_nop 1
	v_permlane32_swap_b32_e32 v100, v101
	v_add_f32_e32 v100, v100, v101
	v_fmamk_f32 v100, v100, 0x3a800000, v155
	v_rsq_f32_e32 v102, v100
	v_mad_i64_i32 v[100:101], s[24:25], v104, s53, v[112:113]
	v_lshl_add_u64 v[100:101], v[100:101], 0, v[114:115]
	global_store_dwordx4 v[100:101], v[96:99], off
	v_pk_mul_f32 v[50:51], v[50:51], v[54:55]
	v_pk_mul_f32 v[40:41], v[40:41], v[44:45]
	v_mul_f32_e32 v96, 0xbfb8aa3b, v102
	v_pk_mul_f32 v[98:99], v[92:93], v[96:97] op_sel_hi:[1,0]
	v_pk_mul_f32 v[42:43], v[42:43], v[46:47]
	v_exp_f32_e32 v97, v98
	v_mul_f32_e32 v98, v102, v102
	v_exp_f32_e32 v99, v99
	v_pk_mul_f32 v[32:33], v[32:33], v[36:37]
	v_pk_mul_f32 v[100:101], v[94:95], v[96:97] op_sel_hi:[1,0]
	v_add_f32_e32 v97, 1.0, v97
	v_rcp_f32_e32 v102, v97
	v_exp_f32_e32 v97, v100
	v_exp_f32_e32 v101, v101
	v_add_f32_e32 v99, 1.0, v99
	v_rcp_f32_e32 v103, v99
	v_add_f32_e32 v97, 1.0, v97
	v_rcp_f32_e32 v100, v97
	v_add_f32_e32 v97, 1.0, v101
	v_rcp_f32_e32 v101, v97
	v_pk_mul_f32 v[92:93], v[98:99], v[102:103] op_sel_hi:[0,1]
	v_pk_mul_f32 v[88:89], v[88:89], v[92:93]
	v_pk_mul_f32 v[92:93], v[86:87], v[96:97] op_sel_hi:[1,0]
	v_pk_mul_f32 v[94:95], v[98:99], v[100:101] op_sel_hi:[0,1]
	v_pk_mul_f32 v[90:91], v[90:91], v[94:95]
	v_pk_mul_f32 v[94:95], v[84:85], v[96:97] op_sel_hi:[1,0]
	v_exp_f32_e32 v92, v92
	v_exp_f32_e32 v94, v94
	v_exp_f32_e32 v95, v95
	v_exp_f32_e32 v93, v93
	v_add_f32_e32 v92, 1.0, v92
	v_add_f32_e32 v94, 1.0, v94
	v_add_f32_e32 v95, 1.0, v95
	v_add_f32_e32 v93, 1.0, v93
	v_rcp_f32_e32 v94, v94
	v_rcp_f32_e32 v95, v95
	v_rcp_f32_e32 v92, v92
	v_rcp_f32_e32 v93, v93
	v_pk_mul_f32 v[34:35], v[34:35], v[38:39]
	v_pk_mul_f32 v[84:85], v[98:99], v[94:95] op_sel_hi:[0,1]
	v_pk_mul_f32 v[24:25], v[24:25], v[28:29]
	v_pk_mul_f32 v[86:87], v[98:99], v[92:93] op_sel_hi:[0,1]
	v_pk_mul_f32 v[86:87], v[82:83], v[86:87]
	v_pk_mul_f32 v[82:83], v[80:81], v[84:85]
	v_cvt_pk_bf16_f32 v80, v88, v89
	v_cvt_pk_bf16_f32 v81, v90, v91
	v_or_b32_e32 v88, 32, v146
	v_cvt_pk_bf16_f32 v82, v82, v83
	v_cvt_pk_bf16_f32 v83, v86, v87
	v_pk_mul_f32 v[26:27], v[26:27], v[30:31]
	v_pk_mul_f32 v[16:17], v[16:17], v[20:21]
	v_pk_mul_f32 v[18:19], v[18:19], v[22:23]
	v_pk_mul_f32 v[8:9], v[8:9], v[12:13]
	s_waitcnt lgkmcnt(4)
	v_add_f32_e32 v84, v200, v201
	v_add_f32_e32 v85, v202, v203
	v_add_f32_e32 v84, v84, v85
	v_mov_b32_e32 v85, v84
	s_nop 1
	v_permlane16_swap_b32_e32 v84, v85
	v_add_f32_e32 v84, v84, v85
	v_mov_b32_e32 v85, v84
	s_nop 1
	v_permlane32_swap_b32_e32 v84, v85
	v_add_f32_e32 v84, v84, v85
	v_fmamk_f32 v84, v84, 0x3a800000, v155
	v_rsq_f32_e32 v86, v84
	v_mad_i64_i32 v[84:85], s[24:25], v88, s53, v[112:113]
	v_lshl_add_u64 v[84:85], v[84:85], 0, v[114:115]
	global_store_dwordx4 v[84:85], v[80:83], off
	v_pk_mul_f32 v[10:11], v[10:11], v[14:15]
	v_pk_mul_f32 v[0:1], v[0:1], v[4:5]
	v_mul_f32_e32 v80, 0xbfb8aa3b, v86
	v_pk_mul_f32 v[82:83], v[76:77], v[80:81] op_sel_hi:[1,0]
	v_pk_mul_f32 v[2:3], v[2:3], v[6:7]
	v_exp_f32_e32 v81, v82
	v_mul_f32_e32 v82, v86, v86
	v_exp_f32_e32 v83, v83
	s_andn2_b64 vcc, exec, s[4:5]
	v_pk_mul_f32 v[84:85], v[78:79], v[80:81] op_sel_hi:[1,0]
	v_add_f32_e32 v81, 1.0, v81
	v_rcp_f32_e32 v86, v81
	v_exp_f32_e32 v81, v84
	v_exp_f32_e32 v85, v85
	v_add_f32_e32 v83, 1.0, v83
	v_rcp_f32_e32 v87, v83
	v_add_f32_e32 v81, 1.0, v81
	v_rcp_f32_e32 v84, v81
	v_add_f32_e32 v81, 1.0, v85
	v_rcp_f32_e32 v85, v81
	v_pk_mul_f32 v[76:77], v[82:83], v[86:87] op_sel_hi:[0,1]
	v_pk_mul_f32 v[72:73], v[72:73], v[76:77]
	v_pk_mul_f32 v[76:77], v[70:71], v[80:81] op_sel_hi:[1,0]
	v_pk_mul_f32 v[78:79], v[82:83], v[84:85] op_sel_hi:[0,1]
	v_pk_mul_f32 v[74:75], v[74:75], v[78:79]
	v_pk_mul_f32 v[78:79], v[68:69], v[80:81] op_sel_hi:[1,0]
	v_exp_f32_e32 v76, v76
	v_exp_f32_e32 v78, v78
	v_exp_f32_e32 v79, v79
	v_exp_f32_e32 v77, v77
	v_add_f32_e32 v76, 1.0, v76
	v_add_f32_e32 v78, 1.0, v78
	v_add_f32_e32 v79, 1.0, v79
	v_add_f32_e32 v77, 1.0, v77
	v_rcp_f32_e32 v78, v78
	v_rcp_f32_e32 v79, v79
	v_rcp_f32_e32 v76, v76
	v_rcp_f32_e32 v77, v77
	s_mov_b64 s[4:5], -1
	v_pk_mul_f32 v[68:69], v[82:83], v[78:79] op_sel_hi:[0,1]
	v_pk_mul_f32 v[70:71], v[82:83], v[76:77] op_sel_hi:[0,1]
	v_pk_mul_f32 v[70:71], v[66:67], v[70:71]
	v_pk_mul_f32 v[66:67], v[64:65], v[68:69]
	v_cvt_pk_bf16_f32 v64, v72, v73
	v_cvt_pk_bf16_f32 v65, v74, v75
	v_or_b32_e32 v72, 48, v146
	v_cvt_pk_bf16_f32 v66, v66, v67
	v_cvt_pk_bf16_f32 v67, v70, v71
	s_waitcnt lgkmcnt(3)
; #define LAS __attribute__((address_space(3)))
; __device__ __forceinline__ unsigned cvt_pk_bf16(float lo, float hi) { unsigned r; asm volatile("v_cvt_pk_bf16_f32 %0, %1, %2" : "=v"(r) : "v"(lo), "v"(hi)); return r; }
; #define ROW_RS(u, ai, m) row_rs_lds((ai) * 128 + wr * 64 + (m) * 16 + fr, fq)
; #define ROWLOOP for (int ai = 0; ai < 2; ++ai) _Pragma("unroll") for (int m = 0; m < 4; ++m)
; __device__ __forceinline__ float row_rs_lds(int rt, int fq) {
;     extern __shared__ __attribute__((aligned(16))) unsigned char lds_raw_[];
;     const f32x4 v = *(const LAS f32x4*)((LAS unsigned char*)lds_raw_ + RS_OFF + rt * 64 + fq * 16);
;     float s = (v[0] + v[1]) + (v[2] + v[3]);
;     s = red4_sum(s);
;     return __builtin_amdgcn_rsqf(s * (1.0f / D) + EPS);
; }
; __device__ __forceinline__ u32x4 pack8(const f32x4 a, const f32x4 b) {
;     u32x4 w; w.x = cvt_pk_bf16(a[0], a[1]); w.y = cvt_pk_bf16(a[2], a[3]); w.z = cvt_pk_bf16(b[0], b[1]); w.w = cvt_pk_bf16(b[2], b[3]); return w;
; }
;     __device__ __forceinline__ void operator()(const Acc& acc, const Unit& u, int wr, int wc, int fr, int fq) const {
;         const int col0 = u.pn * 128 + wc * 32 + fq * 8;
; #pragma unroll
;         ROWLOOP {
;             const int row = ROW_OF(u, ai, m); const float rs = ROW_RS(u, ai, m); const float c1 = -rs * LOG2E, rs2 = rs * rs;
;             f32x4 o[2];
; #pragma unroll
;             for (int n = 0; n < 2; ++n) {
;                 const f32x4 gv = acc[ai][0][m][n], gu = gv * acc[ai][1][m][n], t = gv * c1; f32x4 r;
; #pragma unroll
;                 for (int e = 0; e < 4; ++e) r[e] = __builtin_amdgcn_rcpf(1.0f + __builtin_amdgcn_exp2f(t[e]));
;                 o[n] = gu * (r * rs2);
;             }
;             *(u32x4*)(act + (size_t)row * FF + col0) = pack8(o[0], o[1]);
;         }
	v_add_f32_e32 v68, v204, v205
	v_add_f32_e32 v69, v206, v207
	v_add_f32_e32 v68, v68, v69
	v_mov_b32_e32 v69, v68
	s_nop 1
	v_permlane16_swap_b32_e32 v68, v69
	v_add_f32_e32 v68, v68, v69
	v_mov_b32_e32 v69, v68
	s_nop 1
	v_permlane32_swap_b32_e32 v68, v69
	v_add_f32_e32 v68, v68, v69
	v_fmamk_f32 v68, v68, 0x3a800000, v155
	v_rsq_f32_e32 v70, v68
	v_mad_i64_i32 v[68:69], s[24:25], v72, s53, v[112:113]
	v_lshl_add_u64 v[68:69], v[68:69], 0, v[114:115]
	global_store_dwordx4 v[68:69], v[64:67], off
	s_nop 1
	v_mul_f32_e32 v64, 0xbfb8aa3b, v70
	v_pk_mul_f32 v[66:67], v[60:61], v[64:65] op_sel_hi:[1,0]
	s_nop 0
	v_exp_f32_e32 v65, v66
	v_mul_f32_e32 v66, v70, v70
	v_exp_f32_e32 v67, v67
	v_pk_mul_f32 v[68:69], v[62:63], v[64:65] op_sel_hi:[1,0]
	v_add_f32_e32 v65, 1.0, v65
	v_rcp_f32_e32 v70, v65
	v_exp_f32_e32 v65, v68
	v_exp_f32_e32 v69, v69
	v_add_f32_e32 v67, 1.0, v67
	v_rcp_f32_e32 v71, v67
	v_add_f32_e32 v65, 1.0, v65
	v_rcp_f32_e32 v68, v65
	v_add_f32_e32 v65, 1.0, v69
	v_rcp_f32_e32 v69, v65
	v_pk_mul_f32 v[60:61], v[66:67], v[70:71] op_sel_hi:[0,1]
	v_pk_mul_f32 v[56:57], v[56:57], v[60:61]
	v_pk_mul_f32 v[60:61], v[54:55], v[64:65] op_sel_hi:[1,0]
	v_pk_mul_f32 v[62:63], v[66:67], v[68:69] op_sel_hi:[0,1]
	v_pk_mul_f32 v[58:59], v[58:59], v[62:63]
	v_pk_mul_f32 v[62:63], v[52:53], v[64:65] op_sel_hi:[1,0]
	v_exp_f32_e32 v60, v60
	v_exp_f32_e32 v62, v62
	v_exp_f32_e32 v63, v63
	v_exp_f32_e32 v61, v61
	v_add_f32_e32 v60, 1.0, v60
	v_add_f32_e32 v62, 1.0, v62
	v_add_f32_e32 v63, 1.0, v63
	v_add_f32_e32 v61, 1.0, v61
	v_rcp_f32_e32 v62, v62
	v_rcp_f32_e32 v63, v63
	v_rcp_f32_e32 v60, v60
	v_rcp_f32_e32 v61, v61
	v_pk_mul_f32 v[52:53], v[66:67], v[62:63] op_sel_hi:[0,1]
	v_pk_mul_f32 v[54:55], v[66:67], v[60:61] op_sel_hi:[0,1]
	v_pk_mul_f32 v[54:55], v[50:51], v[54:55]
	v_pk_mul_f32 v[50:51], v[48:49], v[52:53]
	v_cvt_pk_bf16_f32 v48, v56, v57
	v_cvt_pk_bf16_f32 v49, v58, v59
	v_add_u32_e32 v56, 0x80, v146
	v_cvt_pk_bf16_f32 v50, v50, v51
	v_cvt_pk_bf16_f32 v51, v54, v55
	s_waitcnt lgkmcnt(2)
	v_add_f32_e32 v52, v208, v209
	v_add_f32_e32 v53, v210, v211
	v_add_f32_e32 v52, v52, v53
	v_mov_b32_e32 v53, v52
	s_nop 1
	v_permlane16_swap_b32_e32 v52, v53
	v_add_f32_e32 v52, v52, v53
	v_mov_b32_e32 v53, v52
	s_nop 1
	v_permlane32_swap_b32_e32 v52, v53
	v_add_f32_e32 v52, v52, v53
	v_fmamk_f32 v52, v52, 0x3a800000, v155
	v_rsq_f32_e32 v54, v52
	v_mad_i64_i32 v[52:53], s[24:25], v56, s53, v[112:113]
	v_lshl_add_u64 v[52:53], v[52:53], 0, v[114:115]
	global_store_dwordx4 v[52:53], v[48:51], off
	s_nop 1
	v_mul_f32_e32 v48, 0xbfb8aa3b, v54
	v_pk_mul_f32 v[50:51], v[44:45], v[48:49] op_sel_hi:[1,0]
	s_nop 0
	v_exp_f32_e32 v49, v50
	v_mul_f32_e32 v50, v54, v54
	v_exp_f32_e32 v51, v51
	v_pk_mul_f32 v[52:53], v[46:47], v[48:49] op_sel_hi:[1,0]
	v_add_f32_e32 v49, 1.0, v49
	v_rcp_f32_e32 v54, v49
	v_exp_f32_e32 v49, v52
	v_exp_f32_e32 v53, v53
	v_add_f32_e32 v51, 1.0, v51
	v_rcp_f32_e32 v55, v51
	v_add_f32_e32 v49, 1.0, v49
	v_rcp_f32_e32 v52, v49
	v_add_f32_e32 v49, 1.0, v53
	v_rcp_f32_e32 v53, v49
	v_pk_mul_f32 v[44:45], v[50:51], v[54:55] op_sel_hi:[0,1]
	v_pk_mul_f32 v[40:41], v[40:41], v[44:45]
	v_pk_mul_f32 v[44:45], v[38:39], v[48:49] op_sel_hi:[1,0]
	v_pk_mul_f32 v[46:47], v[50:51], v[52:53] op_sel_hi:[0,1]
	v_pk_mul_f32 v[42:43], v[42:43], v[46:47]
	v_pk_mul_f32 v[46:47], v[36:37], v[48:49] op_sel_hi:[1,0]
	v_exp_f32_e32 v44, v44
	v_exp_f32_e32 v46, v46
	v_exp_f32_e32 v47, v47
	v_exp_f32_e32 v45, v45
	v_add_f32_e32 v44, 1.0, v44
	v_add_f32_e32 v46, 1.0, v46
	v_add_f32_e32 v47, 1.0, v47
	v_add_f32_e32 v45, 1.0, v45
	v_rcp_f32_e32 v46, v46
	v_rcp_f32_e32 v47, v47
	v_rcp_f32_e32 v44, v44
	v_rcp_f32_e32 v45, v45
	v_pk_mul_f32 v[36:37], v[50:51], v[46:47] op_sel_hi:[0,1]
	v_pk_mul_f32 v[38:39], v[50:51], v[44:45] op_sel_hi:[0,1]
	v_pk_mul_f32 v[38:39], v[34:35], v[38:39]
	v_pk_mul_f32 v[34:35], v[32:33], v[36:37]
	v_cvt_pk_bf16_f32 v32, v40, v41
	v_cvt_pk_bf16_f32 v33, v42, v43
	v_add_u32_e32 v40, 0x90, v146
	v_cvt_pk_bf16_f32 v34, v34, v35
	v_cvt_pk_bf16_f32 v35, v38, v39
	s_waitcnt lgkmcnt(1)
; #define LAS __attribute__((address_space(3)))
; __device__ __forceinline__ unsigned cvt_pk_bf16(float lo, float hi) { unsigned r; asm volatile("v_cvt_pk_bf16_f32 %0, %1, %2" : "=v"(r) : "v"(lo), "v"(hi)); return r; }
; #define PG8_BAR __builtin_amdgcn_s_barrier()
; #define ROW_RS(u, ai, m) row_rs_lds((ai) * 128 + wr * 64 + (m) * 16 + fr, fq)
; template <class Epi>
; __device__ __forceinline__ void gemm_phase(LAS unsigned char* lds, const int tid, const Gemm g, const StaticOrder& S, const Epi& E) {
;     ...
;         if (!has_next) break;
; #pragma unroll
;         for (int a = 0; a < 2; ++a)
; #pragma unroll
;             for (int b = 0; b < 2; ++b)
; #pragma unroll
;                 for (int m = 0; m < 4; ++m)
; #pragma unroll
;                     for (int n = 0; n < 2; ++n) acc[a][b][m][n] = (f32x4){0.f, 0.f, 0.f, 0.f};
;         cur = nxt; cA = nA; cB = nB; ++ui;
;         if (wr == 1) PG8_BAR;
; __device__ __forceinline__ float row_rs_lds(int rt, int fq) {
;     extern __shared__ __attribute__((aligned(16))) unsigned char lds_raw_[];
;     const f32x4 v = *(const LAS f32x4*)((LAS unsigned char*)lds_raw_ + RS_OFF + rt * 64 + fq * 16);
;     float s = (v[0] + v[1]) + (v[2] + v[3]);
;     s = red4_sum(s);
;     return __builtin_amdgcn_rsqf(s * (1.0f / D) + EPS);
; }
; __device__ __forceinline__ u32x4 pack8(const f32x4 a, const f32x4 b) {
;     u32x4 w; w.x = cvt_pk_bf16(a[0], a[1]); w.y = cvt_pk_bf16(a[2], a[3]); w.z = cvt_pk_bf16(b[0], b[1]); w.w = cvt_pk_bf16(b[2], b[3]); return w;
; }
;     __device__ __forceinline__ void operator()(const Acc& acc, const Unit& u, int wr, int wc, int fr, int fq) const {
;         const int col0 = u.pn * 128 + wc * 32 + fq * 8;
; #pragma unroll
;         ROWLOOP {
;             const int row = ROW_OF(u, ai, m); const float rs = ROW_RS(u, ai, m); const float c1 = -rs * LOG2E, rs2 = rs * rs;
;             f32x4 o[2];
; #pragma unroll
;             for (int n = 0; n < 2; ++n) {
;                 const f32x4 gv = acc[ai][0][m][n], gu = gv * acc[ai][1][m][n], t = gv * c1; f32x4 r;
; #pragma unroll
;                 for (int e = 0; e < 4; ++e) r[e] = __builtin_amdgcn_rcpf(1.0f + __builtin_amdgcn_exp2f(t[e]));
;                 o[n] = gu * (r * rs2);
;             }
;             *(u32x4*)(act + (size_t)row * FF + col0) = pack8(o[0], o[1]);
;         }
	v_add_f32_e32 v36, v212, v213
	v_add_f32_e32 v37, v214, v215
	v_add_f32_e32 v36, v36, v37
	v_mov_b32_e32 v37, v36
	s_nop 1
	v_permlane16_swap_b32_e32 v36, v37
	v_add_f32_e32 v36, v36, v37
	v_mov_b32_e32 v37, v36
	s_nop 1
	v_permlane32_swap_b32_e32 v36, v37
	v_add_f32_e32 v36, v36, v37
	v_fmamk_f32 v36, v36, 0x3a800000, v155
	v_rsq_f32_e32 v38, v36
	v_mad_i64_i32 v[36:37], s[24:25], v40, s53, v[112:113]
	v_lshl_add_u64 v[36:37], v[36:37], 0, v[114:115]
	global_store_dwordx4 v[36:37], v[32:35], off
	s_nop 1
	v_mul_f32_e32 v32, 0xbfb8aa3b, v38
	v_pk_mul_f32 v[34:35], v[28:29], v[32:33] op_sel_hi:[1,0]
	s_nop 0
	v_exp_f32_e32 v33, v34
	v_mul_f32_e32 v34, v38, v38
	v_exp_f32_e32 v35, v35
	v_pk_mul_f32 v[36:37], v[30:31], v[32:33] op_sel_hi:[1,0]
	v_add_f32_e32 v33, 1.0, v33
	v_rcp_f32_e32 v38, v33
	v_exp_f32_e32 v33, v36
	v_exp_f32_e32 v37, v37
	v_add_f32_e32 v35, 1.0, v35
	v_rcp_f32_e32 v39, v35
	v_add_f32_e32 v33, 1.0, v33
	v_rcp_f32_e32 v36, v33
	v_add_f32_e32 v33, 1.0, v37
	v_rcp_f32_e32 v37, v33
	v_pk_mul_f32 v[28:29], v[34:35], v[38:39] op_sel_hi:[0,1]
	v_pk_mul_f32 v[24:25], v[24:25], v[28:29]
	v_pk_mul_f32 v[28:29], v[22:23], v[32:33] op_sel_hi:[1,0]
	v_pk_mul_f32 v[30:31], v[34:35], v[36:37] op_sel_hi:[0,1]
	v_pk_mul_f32 v[26:27], v[26:27], v[30:31]
	v_pk_mul_f32 v[30:31], v[20:21], v[32:33] op_sel_hi:[1,0]
	v_exp_f32_e32 v28, v28
	v_exp_f32_e32 v30, v30
	v_exp_f32_e32 v31, v31
	v_exp_f32_e32 v29, v29
	v_add_f32_e32 v28, 1.0, v28
	v_add_f32_e32 v30, 1.0, v30
	v_add_f32_e32 v31, 1.0, v31
	v_add_f32_e32 v29, 1.0, v29
	v_rcp_f32_e32 v30, v30
	v_rcp_f32_e32 v31, v31
	v_rcp_f32_e32 v28, v28
	v_rcp_f32_e32 v29, v29
	v_pk_mul_f32 v[20:21], v[34:35], v[30:31] op_sel_hi:[0,1]
	v_pk_mul_f32 v[22:23], v[34:35], v[28:29] op_sel_hi:[0,1]
	v_pk_mul_f32 v[22:23], v[18:19], v[22:23]
	v_pk_mul_f32 v[18:19], v[16:17], v[20:21]
	v_cvt_pk_bf16_f32 v16, v24, v25
	v_cvt_pk_bf16_f32 v17, v26, v27
	v_add_u32_e32 v24, 0xa0, v146
	v_cvt_pk_bf16_f32 v18, v18, v19
	v_cvt_pk_bf16_f32 v19, v22, v23
	s_waitcnt lgkmcnt(0)
	v_add_f32_e32 v20, v216, v217
	v_add_f32_e32 v21, v218, v219
	v_add_f32_e32 v20, v20, v21
	v_mov_b32_e32 v21, v20
	s_nop 1
	v_permlane16_swap_b32_e32 v20, v21
	v_add_f32_e32 v20, v20, v21
	v_mov_b32_e32 v21, v20
	s_nop 1
	v_permlane32_swap_b32_e32 v20, v21
	v_add_f32_e32 v20, v20, v21
	v_fmamk_f32 v20, v20, 0x3a800000, v155
	v_rsq_f32_e32 v22, v20
	v_mad_i64_i32 v[20:21], s[24:25], v24, s53, v[112:113]
	v_lshl_add_u64 v[20:21], v[20:21], 0, v[114:115]
	global_store_dwordx4 v[20:21], v[16:19], off
	s_nop 1
	v_mul_f32_e32 v16, 0xbfb8aa3b, v22
	v_pk_mul_f32 v[18:19], v[12:13], v[16:17] op_sel_hi:[1,0]
	s_nop 0
	v_exp_f32_e32 v17, v18
	v_mul_f32_e32 v18, v22, v22
	v_exp_f32_e32 v19, v19
	v_pk_mul_f32 v[20:21], v[14:15], v[16:17] op_sel_hi:[1,0]
	v_add_f32_e32 v17, 1.0, v17
	v_rcp_f32_e32 v22, v17
	v_exp_f32_e32 v17, v20
	v_exp_f32_e32 v21, v21
	v_add_f32_e32 v19, 1.0, v19
	v_rcp_f32_e32 v23, v19
	v_add_f32_e32 v17, 1.0, v17
	v_rcp_f32_e32 v20, v17
	v_add_f32_e32 v17, 1.0, v21
	v_rcp_f32_e32 v21, v17
	v_pk_mul_f32 v[12:13], v[18:19], v[22:23] op_sel_hi:[0,1]
	v_pk_mul_f32 v[8:9], v[8:9], v[12:13]
	v_pk_mul_f32 v[12:13], v[6:7], v[16:17] op_sel_hi:[1,0]
	v_pk_mul_f32 v[14:15], v[18:19], v[20:21] op_sel_hi:[0,1]
	v_pk_mul_f32 v[10:11], v[10:11], v[14:15]
	v_pk_mul_f32 v[14:15], v[4:5], v[16:17] op_sel_hi:[1,0]
	v_exp_f32_e32 v12, v12
	v_exp_f32_e32 v14, v14
	v_exp_f32_e32 v15, v15
	v_exp_f32_e32 v13, v13
	v_add_f32_e32 v12, 1.0, v12
	v_add_f32_e32 v14, 1.0, v14
	v_add_f32_e32 v15, 1.0, v15
	v_add_f32_e32 v13, 1.0, v13
	v_rcp_f32_e32 v14, v14
	v_rcp_f32_e32 v15, v15
	v_rcp_f32_e32 v12, v12
	v_rcp_f32_e32 v13, v13
	v_pk_mul_f32 v[4:5], v[18:19], v[14:15] op_sel_hi:[0,1]
	v_pk_mul_f32 v[6:7], v[18:19], v[12:13] op_sel_hi:[0,1]
	v_pk_mul_f32 v[6:7], v[2:3], v[6:7]
	v_pk_mul_f32 v[2:3], v[0:1], v[4:5]
	v_add_u32_e32 v4, 0xb0, v146
	v_mad_i64_i32 v[4:5], s[24:25], v4, s53, v[112:113]
	v_lshl_add_u64 v[4:5], v[4:5], 0, v[114:115]
	v_cvt_pk_bf16_f32 v0, v8, v9
	v_cvt_pk_bf16_f32 v1, v10, v11
	v_cvt_pk_bf16_f32 v2, v2, v3
	v_cvt_pk_bf16_f32 v3, v6, v7
	global_store_dwordx4 v[4:5], v[0:3], off
	s_cbranch_vccnz .LBB0_258
	s_andn2_b64 vcc, exec, s[8:9]
	s_cbranch_vccnz .LBB0_257
	s_barrier
	s_branch .LBB0_257
